# diff+dilated attention: K/V tiles staged global->LDS by LDS-DMA at the top of the tile iteration (no register staging, no ds_write before the tile barrier)
# speedup vs baseline: 1.0017x; 1.0017x over previous
; #define LAS __attribute__((address_space(3)))
; template <int MODE, int NQ>
; __device__ __forceinline__ void attn_unit(LAS unsigned char* lds, const Params& P, int layer, int b, int h, int qb) {
;     ...
;     for (int it = 0; it < NT; ++it) {
;         const int kt = AT_TILE(it);
;         const int bnx = (bcur == 2) ? 0 : bcur + 1, bn2 = (bnx == 2) ? 0 : bnx + 1;
;         const LAS unsigned char* cur = lds + bcur * AT_BUF;
;         const LAS unsigned char* nxt = lds + bnx * AT_BUF;
; #pragma unroll
;         for (int hf = 0; hf < 2; ++hf) {
;             if (it + 2 < NT) { if (hf == 0) AT_GLOADK(AT_TILE(it + 2)); else AT_GLOADV(AT_TILE(it + 2)); }
;             f32x16 sc[NC];
; #pragma unroll
;             for (int cc = 0; cc < NC; ++cc) {
;                 sc[cc] = f32x16{};
; #pragma unroll
;                 for (int d0 = 0; d0 < ND0; ++d0) sc[cc] = __builtin_amdgcn_mfma_f32_32x32x16_bf16(kf[(cc % NMAP) * ND0 + d0], qf[cc][d0], sc[cc], 0, 0, 0);
;             }
;             __builtin_amdgcn_sched_barrier(0);
;             AT_VLOAD(cur, hf);
;             if (hf == 0) AT_KLOAD(cur, 1); else if (it + 1 < NT) AT_KLOAD(nxt, 0);
;             __builtin_amdgcn_sched_barrier(0);
;             bf16x8 pw[NC][2]; float rmrel[NC]; bool alive = false;
; #pragma unroll
;             for (int cc = 0; cc < NC; ++cc) {
;                 f32x16& s0 = sc[cc];
;                 float mn;
;                 if (MODE != 0) {
;                     const LAS f32x4* tp4 = (const LAS f32x4*)(tlane + (kt * 64 + hf * 32) * 4);
;                     float rm = -3e38f;
; #pragma unroll
;                     for (int g = 0; g < 4; ++g) { const f32x4 t4 = tp4[2 * g];
; #pragma unroll
;                         for (int i = 0; i < 4; ++i) { s0[4 * g + i] = s0[4 * g + i] * c + t4[i]; rm = fmaxf(rm, s0[4 * g + i]); } }
;                     rm = xmax(rm);
;                     mn = fmaxf(mrun[cc], rm);
;                     rmrel[cc] = rm;
;                 } else {
;                     float rm = -3e38f;
; #pragma unroll
;                     for (int r = 0; r < 16; ++r) rm = fmaxf(rm, s0[r]);
;                     rm = xmax(rm);
;                     mn = fmaxf(mrun[cc], rm * c);
;                 }
;                 if (__any(mn > mrun[cc] + AT_THR)) {
;                     const float al = fast_exp2(mrun[cc] - mn); lrun[cc] *= al;
; #pragma unroll
.LBB0_409:
	s_addk_i32 s8, 0x100
	s_add_i32 s7, s7, 1
	s_cmpk_eq_i32 s8, 0x1e00
	s_waitcnt vmcnt(0)
	s_waitcnt lgkmcnt(0)
	s_barrier
	s_cbranch_scc1 .LBB0_434
.LBB0_410:
	s_mul_i32 s10, s9, 0x5000
	s_add_i32 s16, s10, 0
	s_add_i32 s10, s5, s8
	s_add_i32 s11, s10, 0xffffe000
	s_cmp_gt_u32 s7, 31
	v_add3_u32 v0, s16, v193, v192
	s_cselect_b32 s10, s11, s10
	v_add_u32_e32 v199, v0, v189
	v_add_u32_e32 v0, s10, v191
	s_add_i32 s10, s7, 2
	s_sub_i32 s11, s7, 30
	s_cmp_gt_u32 s10, 31
	s_cselect_b32 s10, s11, s10
	s_ashr_i32 s11, s10, 31
	s_lshl_b64 s[10:11], s[10:11], 6
	v_lshl_add_u64 v[2:3], v[182:183], 0, s[10:11]
	v_mov_b64_e32 v[4:5], s[0:1]
	v_mad_u64_u32 v[4:5], s[14:15], v2, s27, v[4:5]
	v_mad_i32_i24 v5, v3, s27, v5
	v_lshl_add_u64 v[228:229], v[178:179], 0, s[10:11]
	v_mad_u64_u32 v[230:231], s[14:15], v228, s27, v[180:181]
	v_mad_i32_i24 v231, v229, s27, v231
	s_nop 1
	s_add_i32 s15, s16, 0xa000
	s_cmp_ge_u32 s15, 0xf000
	s_cselect_b32 s14, 0xf000, 0
	s_sub_i32 s15, s15, s14
	v_readfirstlane_b32 s14, v194
	s_nop 1
	s_add_i32 s14, s14, s15
	s_mov_b32 m0, s14
	s_nop 0
	global_load_lds_dwordx4 v[4:5], off
	s_add_i32 m0, s14, 0x3000
	s_nop 0
	global_load_lds_dwordx4 v[230:231], off
	s_waitcnt lgkmcnt(3)
	v_mfma_f32_32x32x16_bf16 v[96:111], v[140:143], v[124:127], 0
	s_waitcnt lgkmcnt(1)
	v_mfma_f32_32x32x16_bf16 v[80:95], v[132:135], v[120:123], 0
	v_mfma_f32_32x32x16_bf16 v[96:111], v[136:139], v[116:119], v[96:111]
	s_waitcnt lgkmcnt(0)
	v_mfma_f32_32x32x16_bf16 v[80:95], v[128:131], v[112:115], v[80:95]
	ds_read_b64_tr_b16 v[148:149], v199 offset:12288
	ds_read_b64_tr_b16 v[150:151], v199 offset:12800
	ds_read_b64_tr_b16 v[144:145], v199 offset:13312
	ds_read_b64_tr_b16 v[146:147], v199 offset:13824
	ds_read_b64_tr_b16 v[140:141], v199 offset:16384
	ds_read_b64_tr_b16 v[142:143], v199 offset:16896
	ds_read_b64_tr_b16 v[136:137], v199 offset:17408
	ds_read_b64_tr_b16 v[138:139], v199 offset:17920
	v_add3_u32 v6, s16, v195, v196
	ds_read_b128 v[132:135], v6 offset:512
	ds_read_b128 v[128:131], v6 offset:2560
	ds_read_b128 v[10:13], v6 offset:4608
	ds_read_b128 v[6:9], v6 offset:6656
	ds_read_b128 v[156:159], v0 offset:61440
	ds_read_b128 v[152:155], v0 offset:61472
	ds_read_b128 v[164:167], v0 offset:61504
	ds_read_b128 v[172:175], v0 offset:61536
	s_waitcnt lgkmcnt(3)
	v_pk_fma_f32 v[160:161], v[96:97], s[34:35], v[156:157] op_sel_hi:[1,0,1]
	v_pk_fma_f32 v[98:99], v[98:99], s[34:35], v[158:159] op_sel_hi:[1,0,1]
	v_max3_f32 v96, v160, s68, v161
	s_waitcnt lgkmcnt(2)
	v_pk_fma_f32 v[14:15], v[100:101], s[34:35], v[152:153] op_sel_hi:[1,0,1]
	v_max3_f32 v96, v96, v98, v99
	v_max3_f32 v100, v96, v14, v15
	v_pk_fma_f32 v[96:97], v[102:103], s[34:35], v[154:155] op_sel_hi:[1,0,1]
	s_waitcnt lgkmcnt(1)
	v_pk_fma_f32 v[104:105], v[104:105], s[34:35], v[164:165] op_sel_hi:[1,0,1]
	v_max3_f32 v100, v100, v96, v97
	v_max3_f32 v102, v100, v104, v105
	v_pk_fma_f32 v[100:101], v[106:107], s[34:35], v[166:167] op_sel_hi:[1,0,1]
	s_nop 0
	v_max3_f32 v106, v102, v100, v101
	s_waitcnt lgkmcnt(0)
	v_pk_fma_f32 v[102:103], v[108:109], s[34:35], v[172:173] op_sel_hi:[1,0,1]
	s_nop 0
	v_max3_f32 v108, v106, v102, v103
	v_pk_fma_f32 v[106:107], v[110:111], s[34:35], v[174:175] op_sel_hi:[1,0,1]
	s_nop 0
	v_max3_f32 v108, v108, v106, v107
	v_mov_b32_e32 v109, v108
	s_nop 1
	v_permlane32_swap_b32_e32 v108, v109
	v_max_f32_e32 v108, v108, v109
	v_max_f32_e32 v200, v198, v108
	v_add_f32_e32 v109, 0x41000000, v198
	v_cmp_gt_f32_e32 vcc, v200, v109
	s_cbranch_vccz .LBB0_412
	v_sub_f32_e32 v109, v198, v200
	s_mov_b32 s61, 0
	v_exp_f32_e32 v110, v109
	s_nop 0
	v_mul_f32_e32 v188, v188, v110
	v_pk_mul_f32 v[78:79], v[78:79], v[110:111] op_sel_hi:[1,0]
	v_pk_mul_f32 v[76:77], v[76:77], v[110:111] op_sel_hi:[1,0]
	v_pk_mul_f32 v[74:75], v[74:75], v[110:111] op_sel_hi:[1,0]
	v_pk_mul_f32 v[72:73], v[72:73], v[110:111] op_sel_hi:[1,0]
	v_pk_mul_f32 v[70:71], v[70:71], v[110:111] op_sel_hi:[1,0]
	v_pk_mul_f32 v[68:69], v[68:69], v[110:111] op_sel_hi:[1,0]
	v_pk_mul_f32 v[66:67], v[66:67], v[110:111] op_sel_hi:[1,0]
	v_pk_mul_f32 v[64:65], v[64:65], v[110:111] op_sel_hi:[1,0]
	v_pk_mul_f32 v[30:31], v[30:31], v[110:111] op_sel_hi:[1,0]
	v_pk_mul_f32 v[28:29], v[28:29], v[110:111] op_sel_hi:[1,0]
	v_pk_mul_f32 v[26:27], v[26:27], v[110:111] op_sel_hi:[1,0]
	v_pk_mul_f32 v[24:25], v[24:25], v[110:111] op_sel_hi:[1,0]
	v_pk_mul_f32 v[22:23], v[22:23], v[110:111] op_sel_hi:[1,0]
	v_pk_mul_f32 v[20:21], v[20:21], v[110:111] op_sel_hi:[1,0]
	v_pk_mul_f32 v[18:19], v[18:19], v[110:111] op_sel_hi:[1,0]
	v_pk_mul_f32 v[16:17], v[16:17], v[110:111] op_sel_hi:[1,0]
	s_branch .LBB0_413

; #define AT_GLOADK(kt) do { const size_t r_ = rowbase + (size_t)(kt) * 64; \
;         kreg = *(const u32x4*)(Kp + (r_ + lane) * kpitch + wave * 8); \
;         if (MODE == 0 && wave < 4) kreg2 = *(const u32x4*)(proj + (r_ + lane) * NPROJ + 1920 + wave * 8); } while (0)
; #define AT_GLOADV(kt) do { const size_t r_ = rowbase + (size_t)(kt) * 64; \
;         vreg = *(const u32x4*)(Vp + (r_ + 16 * (wave & 3) + (lane >> 2)) * vpitch + (wave >> 2) * 32 + (lane & 3) * 8); } while (0)
; template <int MODE, int NQ>
; __device__ __forceinline__ void attn_unit(LAS unsigned char* lds, const Params& P, int layer, int b, int h, int qb) {
;     ...
;             if (it + 2 < NT) { if (hf == 0) AT_GLOADK(AT_TILE(it + 2)); else AT_GLOADV(AT_TILE(it + 2)); }
.LBB0_503:
	s_add_i32 s16, s8, s18
	s_cmp_lt_u32 s18, s6
	s_cselect_b64 s[10:11], -1, 0
	s_cmp_ge_i32 s16, s6
	s_cselect_b32 s14, s6, 0
	s_add_i32 s15, s7, s18
	s_sub_i32 s14, s15, s14
	s_ashr_i32 s15, s14, 31
	s_lshl_b64 s[14:15], s[14:15], 6
	s_cmp_ge_u32 s18, s6
	s_cbranch_scc1 .LBB0_505
	v_lshl_add_u64 v[2:3], v[122:123], 0, s[14:15]
	v_mov_b64_e32 v[4:5], s[0:1]
	v_mad_u64_u32 v[4:5], s[20:21], v2, s27, v[4:5]
	v_mad_i32_i24 v5, v3, s27, v5
	v_lshl_add_u64 v[2:3], v[118:119], 0, s[14:15]
	v_mad_u64_u32 v[80:81], s[20:21], v2, s27, v[120:121]
	v_mad_i32_i24 v81, v3, s27, v81
	s_nop 1
	s_mul_i32 s21, s19, 0x5000
	s_add_i32 s21, s21, 0xa000
	s_cmp_ge_u32 s21, 0xf000
	s_cselect_b32 s20, 0xf000, 0
	s_sub_i32 s21, s21, s20
	v_readfirstlane_b32 s20, v125
	s_nop 1
	s_add_i32 s20, s20, s21
	s_mov_b32 m0, s20
	s_nop 0
	global_load_lds_dwordx4 v[4:5], off
	s_add_i32 m0, s20, 0x3000
	s_nop 0
	global_load_lds_dwordx4 v[80:81], off

; #define AT_LSTOREK(buf) do { LAS unsigned char* d_ = lds + (buf) * AT_BUF; \
;         *(LAS u32x4*)(d_ + wave * 1024 + lane * 16) = kreg; \
;         if (MODE == 0 && wave < 4) *(LAS u32x4*)(d_ + (8 + wave) * 1024 + lane * 16) = kreg2; } while (0)
; #define AT_LSTOREV(buf) do { LAS unsigned char* d_ = lds + (buf) * AT_BUF; \
;         *(LAS u32x4*)(d_ + AT_V + wave * 1024 + lane * 16) = vreg; } while (0)
; template <int MODE, int NQ>
; __device__ __forceinline__ void attn_unit(LAS unsigned char* lds, const Params& P, int layer, int b, int h, int qb) {
;     ...
;             if (it + 2 < NT) { if (hf == 0) AT_LSTOREK(bn2); else AT_LSTOREV(bn2); }
;         }
;         __syncthreads();
;         bcur = bnx;
.LBB0_523:
	s_and_b64 vcc, exec, s[42:43]
	s_cbranch_vccnz .LBB0_502
	s_waitcnt vmcnt(0)
	s_branch .LBB0_502
